# v42 + scan C loop: 18 packed f32 mul/add between MFMAs split into scalar pairs (7.5 packed-vs-scalar rule)
# speedup vs baseline: 1.0022x; 1.0022x over previous
.LBB0_580:
	ds_read_b128 v[202:205], v82 offset:128
	ds_read_b128 v[186:189], v82 offset:64
	ds_read_b128 v[182:185], v82
	ds_read_b64_tr_b16 v[170:171], v84 offset:7008
	ds_read_b64_tr_b16 v[30:31], v83
	v_add_u32_e32 v83, 0x3700, v83
	ds_read2st64_b64 v[194:197], v85 offset1:1
	ds_read_b128 v[198:201], v43
	ds_read2_b64 v[190:193], v42 offset0:8 offset1:12
	ds_read_b64_tr_b16 v[162:163], v84 offset:6944
	ds_read2_b64 v[178:181], v42 offset1:4
	ds_read_b64_tr_b16 v[166:167], v84 offset:6976
	ds_read_b64_tr_b16 v[158:159], v84 offset:6912
	ds_read_b64_tr_b16 v[38:39], v84 offset:4608
	s_waitcnt lgkmcnt(12)
	v_mul_f32_e32 v16, v16, v202
	v_mul_f32_e32 v17, v17, v203
	v_add_u32_e32 v202, 0x800, v42
	v_add_u32_e32 v42, 0x3700, v42
	v_mul_f32_e32 v18, v18, v204
	v_mul_f32_e32 v19, v19, v205
	s_waitcnt lgkmcnt(11)
	v_mul_f32_e32 v14, v14, v188
	v_mul_f32_e32 v15, v15, v189
	v_cvt_pk_f16_f32 v189, v18, v19
	v_cvt_pk_f16_f32 v188, v16, v17
	s_waitcnt lgkmcnt(10)
	v_mul_f32_e32 v6, v6, v184
	v_mul_f32_e32 v7, v7, v185
	v_mul_f32_e32 v4, v4, v182
	v_mul_f32_e32 v5, v5, v183
	ds_read2st64_b64 v[182:185], v85 offset0:2 offset1:3
	v_add_u32_e32 v85, 0x3700, v85
	s_waitcnt lgkmcnt(9)
	v_mfma_f32_16x16x16_f16 v[170:173], v[170:171], v[30:31], v[16:19]
	v_mul_f32_e32 v12, v12, v186
	v_mul_f32_e32 v13, v13, v187
	s_waitcnt lgkmcnt(8)
	v_mfma_f32_16x16x16_f16 v[16:19], v[194:195], v[30:31], 0
	s_waitcnt lgkmcnt(7)
	v_mul_f32_e64 v2, v2, v200
	v_mul_f32_e64 v3, v3, v201
	v_mul_f32_e32 v0, v0, v198
	v_mul_f32_e32 v1, v1, v199
	v_cvt_pk_f16_f32 v187, v14, v15
	v_cvt_pk_f16_f32 v186, v12, v13
	v_cvt_pk_f16_f32 v201, v6, v7
	v_cvt_pk_f16_f32 v199, v2, v3
	v_cvt_pk_f16_f32 v200, v4, v5
	v_cvt_pk_f16_f32 v198, v0, v1
	s_waitcnt lgkmcnt(6)
	v_mfma_f32_16x16x32_f16 v[190:193], v[190:193], v[186:189], 0
	s_waitcnt lgkmcnt(5)
	v_mfma_f32_16x16x16_f16 v[162:165], v[162:163], v[30:31], v[4:7]
	s_waitcnt lgkmcnt(4)
	v_mfma_f32_16x16x32_f16 v[4:7], v[178:181], v[198:201], v[16:19]
	s_waitcnt lgkmcnt(3)
	v_mfma_f32_16x16x16_f16 v[12:15], v[166:167], v[30:31], v[12:15]
	ds_read_b64_tr_b16 v[174:175], v84 offset:4640
	ds_read2_b64 v[166:169], v202 offset0:40 offset1:44
	ds_read_b64_tr_b16 v[22:23], v84 offset:4672
	s_nop 3
	v_add_f32_e32 v6, v6, v192
	v_add_f32_e32 v7, v7, v193
	v_add_f32_e32 v4, v4, v190
	v_add_f32_e32 v5, v5, v191
	v_cvt_pk_f16_f32 v35, v6, v7
	v_cvt_pk_f16_f32 v34, v4, v5
	s_waitcnt lgkmcnt(3)
	s_nop 0
	v_mfma_f32_16x16x16_f16 v[4:7], v[184:185], v[34:35], 0
	v_mfma_f32_16x16x16_f16 v[158:161], v[158:159], v[30:31], v[0:3]
	s_nop 6
	s_waitcnt lgkmcnt(1)
	v_mfma_f32_16x16x32_f16 v[0:3], v[166:169], v[186:189], 0
	v_cvt_pk_f16_f32 v19, -v6, -v7
	v_cvt_pk_f16_f32 v18, -v4, -v5
	v_mfma_f32_16x16x16_f16 v[6:9], v[196:197], v[30:31], 0
	s_add_i32 s24, s24, -1
	v_mfma_f32_16x16x16_f16 v[30:33], v[38:39], v[18:19], v[158:161]
	ds_read_b64_tr_b16 v[26:27], v84 offset:4704
	v_add_u32_e32 v84, 0x3700, v84
	ds_read_b128 v[38:41], v43 offset:256
	v_add_u32_e32 v43, 0x3700, v43
	s_nop 0
	ds_read_b128 v[158:161], v82 offset:256
	v_mfma_f32_16x16x16_f16 v[34:37], v[174:175], v[18:19], v[162:165]
	s_waitcnt lgkmcnt(3)
	v_mfma_f32_16x16x16_f16 v[12:15], v[22:23], v[18:19], v[12:15]
	ds_read_b128 v[22:25], v82 offset:320
	ds_read_b128 v[162:165], v82 offset:384
	v_add_u32_e32 v82, 0x3700, v82
	v_mfma_f32_16x16x16_f16 v[166:169], v[182:183], v[18:19], v[0:3]
	s_waitcnt lgkmcnt(2)
	v_mul_f32_e32 v4, v158, v34
	v_mul_f32_e32 v5, v159, v35
	ds_read2_b64 v[0:3], v202 offset0:32 offset1:36
	v_mfma_f32_16x16x16_f16 v[26:29], v[26:27], v[18:19], v[170:173]
	s_waitcnt lgkmcnt(2)
	v_mul_f32_e32 v14, v24, v14
	v_mul_f32_e32 v15, v25, v15
	v_mul_f32_e32 v12, v22, v12
	v_mul_f32_e32 v13, v23, v13
	s_waitcnt lgkmcnt(0)
	v_mfma_f32_16x16x32_f16 v[170:173], v[0:3], v[198:201], v[6:9]
	v_mul_f32_e64 v2, v40, v32
	v_mul_f32_e64 v3, v41, v33
	v_mul_f32_e32 v0, v38, v30
	v_mul_f32_e32 v1, v39, v31
	v_mul_f32_e32 v6, v160, v36
	v_mul_f32_e32 v7, v161, v37
	v_mul_f32_e32 v18, v164, v28
	v_mul_f32_e32 v19, v165, v29
	v_mul_f32_e32 v16, v162, v26
	v_mul_f32_e32 v17, v163, v27
	s_nop 1
	v_add_f32_e32 v20, v170, v166
	v_add_f32_e32 v21, v171, v167
	v_add_f32_e32 v8, v172, v168
	v_add_f32_e32 v9, v173, v169
	ds_write2st64_b32 v86, v20, v21 offset1:1
	ds_write2st64_b32 v86, v8, v9 offset0:2 offset1:3
	v_add_u32_e32 v86, 0x1000, v86
	s_cmp_lg_u32 s24, 0
	s_cbranch_scc1 .LBB0_580
